# grid barrier: follower workgroups spin on the top-level generation word instead of their XCD's relay word (one device-scope round trip less per barrier)
# speedup vs baseline: 1.0013x; 1.0001x over previous
.LBB0_26:
	s_or_b64 exec, exec, s[16:17]
	v_cvt_f32_u32_e32 v6, v4
	s_waitcnt vmcnt(0)
	v_readfirstlane_b32 s2, v5
	v_sub_u32_e32 v5, 0, v4
	v_rcp_iflag_f32_e32 v6, v6
	v_add_u32_e32 v7, s2, v3
	v_mul_f32_e32 v6, 0x4f7ffffe, v6
	v_cvt_u32_f32_e32 v6, v6
	v_mul_lo_u32 v3, v5, v6
	v_mul_hi_u32 v3, v6, v3
	v_add_u32_e32 v3, v6, v3
	v_mul_hi_u32 v3, v7, v3
	v_mul_lo_u32 v5, v3, v4
	v_sub_u32_e32 v5, v7, v5
	v_add_u32_e32 v6, 1, v3
	v_sub_u32_e32 v8, v5, v4
	v_cmp_ge_u32_e32 vcc, v5, v4
	s_nop 1
	v_cndmask_b32_e32 v3, v3, v6, vcc
	v_cndmask_b32_e32 v5, v5, v8, vcc
	v_add_u32_e32 v6, 1, v3
	v_cmp_ge_u32_e32 vcc, v5, v4
	v_add_u32_e32 v5, 1, v7
	s_nop 0
	v_cndmask_b32_e32 v3, v3, v6, vcc
	v_mul_lo_u32 v6, v4, v3
	v_add_u32_e32 v4, v6, v4
	v_cmp_ne_u32_e32 vcc, v5, v4
	s_and_saveexec_b64 s[16:17], vcc
	s_xor_b64 s[16:17], exec, s[16:17]
	s_cbranch_execz .LBB0_40
	v_readlane_b32 s18, v254, 13
	v_readlane_b32 s19, v254, 14
	s_waitcnt lgkmcnt(0)
	s_nop 3
	global_load_dword v2, v196, s[18:19] sc1
	s_waitcnt vmcnt(0)
	v_cmp_eq_u32_e32 vcc, v2, v3
	s_and_saveexec_b64 s[18:19], vcc
	s_cbranch_execz .LBB0_39
	s_mov_b32 s2, 1
	s_mov_b64 s[36:37], 0
	s_branch .LBB0_30

.LBB0_32:
	v_readlane_b32 s42, v254, 13
	v_readlane_b32 s43, v254, 14
	s_add_i32 s2, s2, 1
	s_mov_b64 s[44:45], -1
	s_nop 2
	global_load_dword v2, v196, s[42:43] sc1
	s_waitcnt vmcnt(0)
	v_cmp_ne_u32_e32 vcc, v2, v3
	s_orn2_b64 s[42:43], vcc, exec
	s_branch .LBB0_29
